# first K-iteration peeled with C=0 MFMAs, accumulator zeroing block removed
# speedup vs baseline: 1.0084x; 1.0041x over previous
.LBB0_691:
	s_add_u32 s57, s10, 0x100
	s_addc_u32 vcc_lo, s11, 0
	s_add_u32 s38, s52, 0x80
	s_addc_u32 s39, s53, 0
	s_mov_b32 s10, 0
	s_add_i32 s52, s10, 2
	s_add_u32 s33, s38, 0x80
	s_addc_u32 s11, s39, 0
	s_add_i32 s34, 0, 0x10000
	s_cmp_eq_u32 s95, s10
	s_cselect_b32 s11, s9, s11
	s_cselect_b32 s10, s8, s33
	s_cselect_b32 s73, s1, vcc_lo
	s_cselect_b32 s72, s0, s57
	s_add_i32 s33, 0, 0x14000
	v_add_u32_e32 v156, s34, v223
	v_add_u32_e32 v172, s33, v223
	ds_read_b128 v[130:133], v156
	ds_read_b128 v[134:137], v156 offset:1024
	ds_read_b128 v[138:141], v156 offset:2048
	ds_read_b128 v[156:159], v156 offset:3072
	ds_read_b128 v[160:163], v172
	ds_read_b128 v[164:167], v172 offset:1024
	ds_read_b128 v[168:171], v172 offset:2048
	ds_read_b128 v[172:175], v172 offset:3072
	v_lshl_add_u64 v[230:231], s[38:39], 0, v[154:155]
	s_add_i32 m0, s20, 0xc000
	ds_read_b128 v[176:179], v225
	ds_read_b128 v[180:183], v225 offset:1024
	ds_read_b128 v[184:187], v225 offset:2048
	ds_read_b128 v[188:191], v225 offset:3072
	ds_read_b128 v[192:195], v225 offset:4096
	ds_read_b128 v[196:199], v225 offset:5120
	ds_read_b128 v[200:203], v225 offset:6144
	ds_read_b128 v[226:229], v225 offset:7168
	global_load_lds_dwordx4 v[230:231], off
	v_lshl_add_u64 v[230:231], s[38:39], 0, v[152:153]
	s_add_i32 m0, s20, 0xe000
	s_nop 0
	global_load_lds_dwordx4 v[230:231], off
	s_waitcnt vmcnt(8)
	s_waitcnt lgkmcnt(0)
	s_barrier
	s_setprio 1
	s_waitcnt lgkmcnt(0)
	v_mfma_f32_16x16x32_bf16 v[126:129], v[130:133], v[176:179], 0
	v_mfma_f32_16x16x32_bf16 v[122:125], v[138:141], v[176:179], 0
	v_mfma_f32_16x16x32_bf16 v[110:113], v[130:133], v[184:187], 0
	v_mfma_f32_16x16x32_bf16 v[106:109], v[138:141], v[184:187], 0
	v_mfma_f32_16x16x32_bf16 v[94:97], v[130:133], v[192:195], 0
	v_mfma_f32_16x16x32_bf16 v[90:93], v[138:141], v[192:195], 0
	v_mfma_f32_16x16x32_bf16 v[78:81], v[130:133], v[200:203], 0
	v_mfma_f32_16x16x32_bf16 v[74:77], v[138:141], v[200:203], 0
	v_mfma_f32_16x16x32_bf16 v[126:129], v[134:137], v[180:183], v[126:129]
	v_mfma_f32_16x16x32_bf16 v[122:125], v[156:159], v[180:183], v[122:125]
	v_mfma_f32_16x16x32_bf16 v[110:113], v[134:137], v[188:191], v[110:113]
	v_mfma_f32_16x16x32_bf16 v[106:109], v[156:159], v[188:191], v[106:109]
	v_mfma_f32_16x16x32_bf16 v[94:97], v[134:137], v[196:199], v[94:97]
	v_mfma_f32_16x16x32_bf16 v[90:93], v[156:159], v[196:199], v[90:93]
	v_mfma_f32_16x16x32_bf16 v[78:81], v[134:137], v[226:229], v[78:81]
	v_mfma_f32_16x16x32_bf16 v[74:77], v[156:159], v[226:229], v[74:77]
	s_setprio 0
	s_setprio 1
	v_mfma_f32_16x16x32_bf16 v[118:121], v[160:163], v[176:179], 0
	v_mfma_f32_16x16x32_bf16 v[114:117], v[168:171], v[176:179], 0
	v_mfma_f32_16x16x32_bf16 v[102:105], v[160:163], v[184:187], 0
	v_mfma_f32_16x16x32_bf16 v[98:101], v[168:171], v[184:187], 0
	v_mfma_f32_16x16x32_bf16 v[86:89], v[160:163], v[192:195], 0
	v_mfma_f32_16x16x32_bf16 v[82:85], v[168:171], v[192:195], 0
	v_mfma_f32_16x16x32_bf16 v[70:73], v[160:163], v[200:203], 0
	v_mfma_f32_16x16x32_bf16 v[66:69], v[168:171], v[200:203], 0
	v_mfma_f32_16x16x32_bf16 v[118:121], v[164:167], v[180:183], v[118:121]
	v_mfma_f32_16x16x32_bf16 v[114:117], v[172:175], v[180:183], v[114:117]
	v_mfma_f32_16x16x32_bf16 v[102:105], v[164:167], v[188:191], v[102:105]
	v_mfma_f32_16x16x32_bf16 v[98:101], v[172:175], v[188:191], v[98:101]
	v_mfma_f32_16x16x32_bf16 v[86:89], v[164:167], v[196:199], v[86:89]
	v_mfma_f32_16x16x32_bf16 v[82:85], v[172:175], v[196:199], v[82:85]
	v_mfma_f32_16x16x32_bf16 v[70:73], v[164:167], v[226:229], v[70:73]
	v_mfma_f32_16x16x32_bf16 v[66:69], v[172:175], v[226:229], v[66:69]
	s_setprio 0
	s_barrier
	s_add_i32 s34, s34, s29
	v_lshl_add_u64 v[230:231], s[72:73], 0, v[0:1]
	s_mov_b32 m0, s34
	ds_read_b128 v[176:179], v225 offset:16384
	ds_read_b128 v[180:183], v225 offset:17408
	ds_read_b128 v[184:187], v225 offset:18432
	ds_read_b128 v[188:191], v225 offset:19456
	ds_read_b128 v[192:195], v225 offset:20480
	ds_read_b128 v[196:199], v225 offset:21504
	ds_read_b128 v[200:203], v225 offset:22528
	ds_read_b128 v[226:229], v225 offset:23552
	global_load_lds_dwordx4 v[230:231], off
	s_add_i32 m0, s34, 0x2000
	v_lshl_add_u64 v[232:233], s[72:73], 0, v[150:151]
	s_add_u32 s72, s72, s46
	s_addc_u32 s73, s73, 0
	s_add_i32 s33, s33, s29
	global_load_lds_dwordx4 v[232:233], off
	v_lshl_add_u64 v[234:235], s[72:73], 0, v[0:1]
	s_mov_b32 m0, s33
	v_lshl_add_u64 v[236:237], s[72:73], 0, v[150:151]
	global_load_lds_dwordx4 v[234:235], off
	s_add_i32 m0, s33, 0x2000
	v_lshl_add_u64 v[238:239], s[10:11], 0, v[146:147]
	global_load_lds_dwordx4 v[236:237], off
	s_mov_b32 m0, s20
	v_lshl_add_u64 v[240:241], s[10:11], 0, v[148:149]
	global_load_lds_dwordx4 v[238:239], off
	s_mov_b32 m0, s35
	s_nop 0
	global_load_lds_dwordx4 v[240:241], off
	s_waitcnt vmcnt(8)
	s_waitcnt lgkmcnt(0)
	s_barrier
	s_setprio 1
	s_waitcnt lgkmcnt(0)
	v_mfma_f32_16x16x32_bf16 v[62:65], v[130:133], v[176:179], 0
	v_mfma_f32_16x16x32_bf16 v[58:61], v[138:141], v[176:179], 0
	v_mfma_f32_16x16x32_bf16 v[46:49], v[130:133], v[184:187], 0
	v_mfma_f32_16x16x32_bf16 v[42:45], v[138:141], v[184:187], 0
	v_mfma_f32_16x16x32_bf16 v[30:33], v[130:133], v[192:195], 0
	v_mfma_f32_16x16x32_bf16 v[26:29], v[138:141], v[192:195], 0
	v_mfma_f32_16x16x32_bf16 v[14:17], v[130:133], v[200:203], 0
	v_mfma_f32_16x16x32_bf16 v[10:13], v[138:141], v[200:203], 0
	v_mfma_f32_16x16x32_bf16 v[62:65], v[134:137], v[180:183], v[62:65]
	v_mfma_f32_16x16x32_bf16 v[58:61], v[156:159], v[180:183], v[58:61]
	v_mfma_f32_16x16x32_bf16 v[46:49], v[134:137], v[188:191], v[46:49]
	v_mfma_f32_16x16x32_bf16 v[42:45], v[156:159], v[188:191], v[42:45]
	v_mfma_f32_16x16x32_bf16 v[30:33], v[134:137], v[196:199], v[30:33]
	v_mfma_f32_16x16x32_bf16 v[26:29], v[156:159], v[196:199], v[26:29]
	v_mfma_f32_16x16x32_bf16 v[14:17], v[134:137], v[226:229], v[14:17]
	v_mfma_f32_16x16x32_bf16 v[10:13], v[156:159], v[226:229], v[10:13]
	s_setprio 0
	s_setprio 1
	v_mfma_f32_16x16x32_bf16 v[54:57], v[160:163], v[176:179], 0
	v_mfma_f32_16x16x32_bf16 v[50:53], v[168:171], v[176:179], 0
	v_mfma_f32_16x16x32_bf16 v[38:41], v[160:163], v[184:187], 0
	v_mfma_f32_16x16x32_bf16 v[34:37], v[168:171], v[184:187], 0
	v_mfma_f32_16x16x32_bf16 v[22:25], v[160:163], v[192:195], 0
	v_mfma_f32_16x16x32_bf16 v[18:21], v[168:171], v[192:195], 0
	v_mfma_f32_16x16x32_bf16 v[6:9], v[160:163], v[200:203], 0
	v_mfma_f32_16x16x32_bf16 v[2:5], v[168:171], v[200:203], 0
	v_mfma_f32_16x16x32_bf16 v[54:57], v[164:167], v[180:183], v[54:57]
	v_mfma_f32_16x16x32_bf16 v[50:53], v[172:175], v[180:183], v[50:53]
	v_mfma_f32_16x16x32_bf16 v[38:41], v[164:167], v[188:191], v[38:41]
	v_mfma_f32_16x16x32_bf16 v[34:37], v[172:175], v[188:191], v[34:37]
	v_mfma_f32_16x16x32_bf16 v[22:25], v[164:167], v[196:199], v[22:25]
	v_mfma_f32_16x16x32_bf16 v[18:21], v[172:175], v[196:199], v[18:21]
	v_mfma_f32_16x16x32_bf16 v[6:9], v[164:167], v[226:229], v[6:9]
	v_mfma_f32_16x16x32_bf16 v[2:5], v[172:175], v[226:229], v[2:5]
	s_setprio 0
	s_barrier
	s_add_i32 s33, 0, 0x18000
	s_add_i32 s34, 0, 0x1c000
	v_add_u32_e32 v156, s33, v223
	v_add_u32_e32 v172, s34, v223
	ds_read_b128 v[130:133], v156
	ds_read_b128 v[134:137], v156 offset:1024
	ds_read_b128 v[138:141], v156 offset:2048
	ds_read_b128 v[156:159], v156 offset:3072
	ds_read_b128 v[160:163], v172
	ds_read_b128 v[164:167], v172 offset:1024
	ds_read_b128 v[168:171], v172 offset:2048
	ds_read_b128 v[172:175], v172 offset:3072
	s_add_u32 s10, s10, s46
	s_addc_u32 s11, s11, 0
	s_mov_b32 m0, s93
	v_lshl_add_u64 v[242:243], s[10:11], 0, v[146:147]
	ds_read_b128 v[176:179], v225 offset:32768
	ds_read_b128 v[180:183], v225 offset:33792
	ds_read_b128 v[184:187], v225 offset:34816
	ds_read_b128 v[188:191], v225 offset:35840
	ds_read_b128 v[192:195], v225 offset:36864
	ds_read_b128 v[196:199], v225 offset:37888
	ds_read_b128 v[200:203], v225 offset:38912
	ds_read_b128 v[226:229], v225 offset:39936
	global_load_lds_dwordx4 v[242:243], off
	v_lshl_add_u64 v[242:243], s[10:11], 0, v[148:149]
	s_mov_b32 m0, s83
	s_nop 0
	global_load_lds_dwordx4 v[242:243], off
	s_waitcnt vmcnt(8)
	s_waitcnt lgkmcnt(0)
	s_barrier
	s_setprio 1
	s_waitcnt lgkmcnt(0)
	v_mfma_f32_16x16x32_bf16 v[126:129], v[130:133], v[176:179], v[126:129]
	v_mfma_f32_16x16x32_bf16 v[122:125], v[138:141], v[176:179], v[122:125]
	v_mfma_f32_16x16x32_bf16 v[110:113], v[130:133], v[184:187], v[110:113]
	v_mfma_f32_16x16x32_bf16 v[106:109], v[138:141], v[184:187], v[106:109]
	v_mfma_f32_16x16x32_bf16 v[94:97], v[130:133], v[192:195], v[94:97]
	v_mfma_f32_16x16x32_bf16 v[90:93], v[138:141], v[192:195], v[90:93]
	v_mfma_f32_16x16x32_bf16 v[78:81], v[130:133], v[200:203], v[78:81]
	v_mfma_f32_16x16x32_bf16 v[74:77], v[138:141], v[200:203], v[74:77]
	v_mfma_f32_16x16x32_bf16 v[126:129], v[134:137], v[180:183], v[126:129]
	v_mfma_f32_16x16x32_bf16 v[122:125], v[156:159], v[180:183], v[122:125]
	v_mfma_f32_16x16x32_bf16 v[110:113], v[134:137], v[188:191], v[110:113]
	v_mfma_f32_16x16x32_bf16 v[106:109], v[156:159], v[188:191], v[106:109]
	v_mfma_f32_16x16x32_bf16 v[94:97], v[134:137], v[196:199], v[94:97]
	v_mfma_f32_16x16x32_bf16 v[90:93], v[156:159], v[196:199], v[90:93]
	v_mfma_f32_16x16x32_bf16 v[78:81], v[134:137], v[226:229], v[78:81]
	v_mfma_f32_16x16x32_bf16 v[74:77], v[156:159], v[226:229], v[74:77]
	s_setprio 0
	s_setprio 1
	v_mfma_f32_16x16x32_bf16 v[118:121], v[160:163], v[176:179], v[118:121]
	v_mfma_f32_16x16x32_bf16 v[114:117], v[168:171], v[176:179], v[114:117]
	v_mfma_f32_16x16x32_bf16 v[102:105], v[160:163], v[184:187], v[102:105]
	v_mfma_f32_16x16x32_bf16 v[98:101], v[168:171], v[184:187], v[98:101]
	v_mfma_f32_16x16x32_bf16 v[86:89], v[160:163], v[192:195], v[86:89]
	v_mfma_f32_16x16x32_bf16 v[82:85], v[168:171], v[192:195], v[82:85]
	v_mfma_f32_16x16x32_bf16 v[70:73], v[160:163], v[200:203], v[70:73]
	v_mfma_f32_16x16x32_bf16 v[66:69], v[168:171], v[200:203], v[66:69]
	v_mfma_f32_16x16x32_bf16 v[118:121], v[164:167], v[180:183], v[118:121]
	v_mfma_f32_16x16x32_bf16 v[114:117], v[172:175], v[180:183], v[114:117]
	v_mfma_f32_16x16x32_bf16 v[102:105], v[164:167], v[188:191], v[102:105]
	v_mfma_f32_16x16x32_bf16 v[98:101], v[172:175], v[188:191], v[98:101]
	v_mfma_f32_16x16x32_bf16 v[86:89], v[164:167], v[196:199], v[86:89]
	v_mfma_f32_16x16x32_bf16 v[82:85], v[172:175], v[196:199], v[82:85]
	v_mfma_f32_16x16x32_bf16 v[70:73], v[164:167], v[226:229], v[70:73]
	v_mfma_f32_16x16x32_bf16 v[66:69], v[172:175], v[226:229], v[66:69]
	s_setprio 0
	s_barrier
	s_add_i32 s10, s33, s29
	v_lshl_add_u64 v[230:231], v[230:231], 0, s[14:15]
	s_mov_b32 m0, s10
	ds_read_b128 v[176:179], v225 offset:49152
	ds_read_b128 v[180:183], v225 offset:50176
	ds_read_b128 v[184:187], v225 offset:51200
	ds_read_b128 v[188:191], v225 offset:52224
	ds_read_b128 v[192:195], v225 offset:53248
	ds_read_b128 v[196:199], v225 offset:54272
	ds_read_b128 v[200:203], v225 offset:55296
	ds_read_b128 v[226:229], v225 offset:56320
	global_load_lds_dwordx4 v[230:231], off
	v_lshl_add_u64 v[230:231], v[232:233], 0, s[14:15]
	s_add_i32 m0, s10, 0x2000
	s_add_i32 s10, s34, s29
	global_load_lds_dwordx4 v[230:231], off
	v_lshl_add_u64 v[230:231], v[234:235], 0, s[14:15]
	s_mov_b32 m0, s10
	s_nop 0
	global_load_lds_dwordx4 v[230:231], off
	v_lshl_add_u64 v[230:231], v[236:237], 0, s[14:15]
	s_add_i32 m0, s10, 0x2000
	s_nop 0
	global_load_lds_dwordx4 v[230:231], off
	v_lshl_add_u64 v[230:231], v[238:239], 0, s[14:15]
	s_mov_b32 m0, s96
	s_nop 0
	global_load_lds_dwordx4 v[230:231], off
	v_lshl_add_u64 v[230:231], v[240:241], 0, s[14:15]
	s_mov_b32 m0, s97
	s_nop 0
	global_load_lds_dwordx4 v[230:231], off
	s_waitcnt vmcnt(8)
	s_waitcnt lgkmcnt(0)
	s_barrier
	s_setprio 1
	s_waitcnt lgkmcnt(0)
	v_mfma_f32_16x16x32_bf16 v[62:65], v[130:133], v[176:179], v[62:65]
	v_mfma_f32_16x16x32_bf16 v[58:61], v[138:141], v[176:179], v[58:61]
	v_mfma_f32_16x16x32_bf16 v[46:49], v[130:133], v[184:187], v[46:49]
	v_mfma_f32_16x16x32_bf16 v[42:45], v[138:141], v[184:187], v[42:45]
	v_mfma_f32_16x16x32_bf16 v[30:33], v[130:133], v[192:195], v[30:33]
	v_mfma_f32_16x16x32_bf16 v[26:29], v[138:141], v[192:195], v[26:29]
	v_mfma_f32_16x16x32_bf16 v[14:17], v[130:133], v[200:203], v[14:17]
	v_mfma_f32_16x16x32_bf16 v[10:13], v[138:141], v[200:203], v[10:13]
	v_mfma_f32_16x16x32_bf16 v[62:65], v[134:137], v[180:183], v[62:65]
	v_mfma_f32_16x16x32_bf16 v[58:61], v[156:159], v[180:183], v[58:61]
	v_mfma_f32_16x16x32_bf16 v[46:49], v[134:137], v[188:191], v[46:49]
	v_mfma_f32_16x16x32_bf16 v[42:45], v[156:159], v[188:191], v[42:45]
	v_mfma_f32_16x16x32_bf16 v[30:33], v[134:137], v[196:199], v[30:33]
	v_mfma_f32_16x16x32_bf16 v[26:29], v[156:159], v[196:199], v[26:29]
	v_mfma_f32_16x16x32_bf16 v[14:17], v[134:137], v[226:229], v[14:17]
	v_mfma_f32_16x16x32_bf16 v[10:13], v[156:159], v[226:229], v[10:13]
	s_setprio 0
	s_setprio 1
	v_mfma_f32_16x16x32_bf16 v[54:57], v[160:163], v[176:179], v[54:57]
	v_mfma_f32_16x16x32_bf16 v[50:53], v[168:171], v[176:179], v[50:53]
	v_mfma_f32_16x16x32_bf16 v[38:41], v[160:163], v[184:187], v[38:41]
	v_mfma_f32_16x16x32_bf16 v[34:37], v[168:171], v[184:187], v[34:37]
	v_mfma_f32_16x16x32_bf16 v[22:25], v[160:163], v[192:195], v[22:25]
	v_mfma_f32_16x16x32_bf16 v[18:21], v[168:171], v[192:195], v[18:21]
	v_mfma_f32_16x16x32_bf16 v[6:9], v[160:163], v[200:203], v[6:9]
	v_mfma_f32_16x16x32_bf16 v[2:5], v[168:171], v[200:203], v[2:5]
	v_mfma_f32_16x16x32_bf16 v[54:57], v[164:167], v[180:183], v[54:57]
	v_mfma_f32_16x16x32_bf16 v[50:53], v[172:175], v[180:183], v[50:53]
	v_mfma_f32_16x16x32_bf16 v[38:41], v[164:167], v[188:191], v[38:41]
	v_mfma_f32_16x16x32_bf16 v[34:37], v[172:175], v[188:191], v[34:37]
	v_mfma_f32_16x16x32_bf16 v[22:25], v[164:167], v[196:199], v[22:25]
	v_mfma_f32_16x16x32_bf16 v[18:21], v[172:175], v[196:199], v[18:21]
	v_mfma_f32_16x16x32_bf16 v[6:9], v[164:167], v[226:229], v[6:9]
	v_mfma_f32_16x16x32_bf16 v[2:5], v[172:175], v[226:229], v[2:5]
	s_setprio 0
	s_barrier
	s_add_u32 s57, s57, 0x100
	s_addc_u32 vcc_lo, vcc_lo, 0
	s_add_u32 s38, s38, 0x100
	s_addc_u32 s39, s39, 0
	s_cmp_ge_u32 s52, s22
	s_mov_b32 s10, s52
	s_cbranch_scc0 .LBB0_692
	s_branch .Lkloop_exit

.Lkloop_exit:
	s_and_b64 vcc, exec, s[6:7]
	s_cbranch_vccz .LBB0_695
	s_barrier
